# workspace pointer lane reads also at the 14 grid-barrier entries (no kernarg flat_load on the barrier path)
# speedup vs baseline: 1.0029x; 1.0029x over previous
.LBB0_203:
	s_mov_b64 s[6:7], s[0:1]
	s_waitcnt vmcnt(0) lgkmcnt(0)
	v_mov_b64_e32 v[0:1], s[6:7]
	v_readlane_b32 s100, v254, 3
	v_readlane_b32 s101, v254, 4
	s_nop 0
	v_mov_b32_e32 v0, s100
	v_mov_b32_e32 v1, s101
	s_getreg_b32 s3, hwreg(HW_REG_XCC_ID, 0, 4)
	s_waitcnt vmcnt(0)
	s_waitcnt lgkmcnt(0)
	s_barrier
	v_readlane_b32 s98, v254, 2
	v_readfirstlane_b32 s100, v176
	s_nop 0
	s_lshr_b32 s100, s100, 6
	s_cmp_eq_u32 s100, 1
	s_cselect_b32 s100, s98, 0
	s_cmp_lg_u32 s100, 0
	s_cbranch_scc0 .Lew_1
	buffer_inv sc1
	s_waitcnt vmcnt(0)

.LBB0_268:
	s_mov_b64 s[6:7], s[0:1]
	s_nop 0
	v_mov_b64_e32 v[0:1], s[6:7]
	v_readlane_b32 s100, v254, 3
	v_readlane_b32 s101, v254, 4
	s_nop 0
	v_mov_b32_e32 v0, s100
	v_mov_b32_e32 v1, s101
	s_getreg_b32 s3, hwreg(HW_REG_XCC_ID, 0, 4)
	s_waitcnt vmcnt(0)
	s_waitcnt vmcnt(0) lgkmcnt(0)
	s_barrier
	v_readlane_b32 s98, v254, 2
	v_readfirstlane_b32 s100, v176
	s_nop 0
	s_lshr_b32 s100, s100, 6
	s_cmp_eq_u32 s100, 1
	s_cselect_b32 s100, s98, 0
	s_cmp_lg_u32 s100, 0
	s_cbranch_scc0 .Lew_2
	buffer_inv sc1
	s_waitcnt vmcnt(0)

.LBB0_334:
	v_writelane_b32 v255, s11, 0
	v_writelane_b32 v255, s12, 1
	v_writelane_b32 v255, s13, 2
	v_writelane_b32 v255, s14, 3
	v_writelane_b32 v255, s15, 4
	v_writelane_b32 v255, s16, 5
	v_writelane_b32 v255, s17, 6
	v_writelane_b32 v255, s20, 7
	v_writelane_b32 v255, s21, 8
	v_writelane_b32 v255, s22, 9
	v_writelane_b32 v255, s23, 10
	v_writelane_b32 v255, s28, 11
	v_writelane_b32 v255, s30, 12
	v_writelane_b32 v255, s34, 13
	v_writelane_b32 v255, s38, 14
	s_mov_b64 s[6:7], s[0:1]
	s_waitcnt lgkmcnt(0)
	s_barrier
	s_nop 0
	v_mov_b64_e32 v[0:1], s[6:7]
	v_readlane_b32 s100, v254, 3
	v_readlane_b32 s101, v254, 4
	s_nop 0
	v_mov_b32_e32 v0, s100
	v_mov_b32_e32 v1, s101
	s_getreg_b32 s3, hwreg(HW_REG_XCC_ID, 0, 4)
	s_waitcnt vmcnt(0)
	s_waitcnt lgkmcnt(0)
	s_barrier
	v_readlane_b32 s98, v254, 2
	v_readfirstlane_b32 s100, v176
	s_nop 0
	s_lshr_b32 s100, s100, 6
	s_cmp_eq_u32 s100, 1
	s_cselect_b32 s100, s98, 0
	s_cmp_lg_u32 s100, 0
	s_cbranch_scc0 .Lb20_ew_3
	buffer_inv sc1
	s_waitcnt vmcnt(0)

.LBB0_367:
	s_mov_b64 s[6:7], s[0:1]
	s_waitcnt lgkmcnt(0)
	s_barrier
	s_nop 0
	v_mov_b64_e32 v[0:1], s[6:7]
	v_readlane_b32 s100, v254, 3
	v_readlane_b32 s101, v254, 4
	s_nop 0
	v_mov_b32_e32 v0, s100
	v_mov_b32_e32 v1, s101
	s_getreg_b32 s3, hwreg(HW_REG_XCC_ID, 0, 4)
	s_waitcnt vmcnt(0)
	s_waitcnt lgkmcnt(0)
	s_barrier
	v_readlane_b32 s98, v254, 2
	v_readfirstlane_b32 s100, v176
	s_nop 0
	s_lshr_b32 s100, s100, 6
	s_cmp_eq_u32 s100, 1
	s_cselect_b32 s100, s98, 0
	s_cmp_lg_u32 s100, 0
	s_cbranch_scc0 .Lew_3
	buffer_inv sc1
	s_waitcnt vmcnt(0)

.LBB0_445:
	s_mov_b64 s[6:7], s[0:1]
	s_nop 0
	v_mov_b64_e32 v[0:1], s[6:7]
	v_readlane_b32 s100, v254, 3
	v_readlane_b32 s101, v254, 4
	s_nop 0
	v_mov_b32_e32 v0, s100
	v_mov_b32_e32 v1, s101
	s_getreg_b32 s3, hwreg(HW_REG_XCC_ID, 0, 4)
	s_waitcnt vmcnt(0)
	s_waitcnt lgkmcnt(0)
	s_barrier
	v_readlane_b32 s98, v254, 2
	v_readfirstlane_b32 s100, v176
	s_nop 0
	s_lshr_b32 s100, s100, 6
	s_cmp_eq_u32 s100, 1
	s_cselect_b32 s100, s98, 0
	s_cmp_lg_u32 s100, 0
	s_cbranch_scc0 .Lew_4
	buffer_inv sc1
	s_waitcnt vmcnt(0)

.LBB0_629:
	s_mov_b64 s[8:9], s[0:1]
	s_nop 0
	v_mov_b64_e32 v[0:1], s[8:9]
	v_readlane_b32 s100, v254, 3
	v_readlane_b32 s101, v254, 4
	s_nop 0
	v_mov_b32_e32 v0, s100
	v_mov_b32_e32 v1, s101
	s_getreg_b32 s3, hwreg(HW_REG_XCC_ID, 0, 4)
	s_waitcnt vmcnt(0)
	s_waitcnt vmcnt(0) lgkmcnt(0)
	s_barrier
	v_readlane_b32 s98, v254, 2
	v_readfirstlane_b32 s100, v176
	s_nop 0
	s_lshr_b32 s100, s100, 6
	s_cmp_eq_u32 s100, 1
	s_cselect_b32 s100, s98, 0
	s_cmp_lg_u32 s100, 0
	s_cbranch_scc0 .Lew_6
	buffer_inv sc1
	s_waitcnt vmcnt(0)

.LBB0_752:
	s_mov_b64 s[8:9], s[0:1]
	s_waitcnt vmcnt(0) lgkmcnt(0)
	v_mov_b64_e32 v[0:1], s[8:9]
	v_readlane_b32 s100, v254, 3
	v_readlane_b32 s101, v254, 4
	s_nop 0
	v_mov_b32_e32 v0, s100
	v_mov_b32_e32 v1, s101
	s_getreg_b32 s3, hwreg(HW_REG_XCC_ID, 0, 4)
	s_waitcnt vmcnt(0)
	s_waitcnt lgkmcnt(0)
	s_barrier
	v_readlane_b32 s98, v254, 2
	v_readfirstlane_b32 s100, v176
	s_nop 0
	s_lshr_b32 s100, s100, 6
	s_cmp_eq_u32 s100, 1
	s_cselect_b32 s100, s98, 0
	s_cmp_lg_u32 s100, 0
	s_cbranch_scc0 .Lew_7
	buffer_inv sc1
	s_waitcnt vmcnt(0)

.LBB0_1071:
	v_writelane_b32 v255, s11, 0
	v_writelane_b32 v255, s12, 1
	v_writelane_b32 v255, s13, 2
	v_writelane_b32 v255, s14, 3
	v_writelane_b32 v255, s15, 4
	v_writelane_b32 v255, s16, 5
	v_writelane_b32 v255, s17, 6
	v_writelane_b32 v255, s21, 7
	v_writelane_b32 v255, s22, 8
	v_writelane_b32 v255, s23, 9
	v_writelane_b32 v255, s26, 10
	v_writelane_b32 v255, s28, 11
	v_writelane_b32 v255, s34, 12
	s_mov_b64 s[8:9], s[0:1]
	s_waitcnt lgkmcnt(0)
	s_barrier
	s_nop 0
	v_mov_b64_e32 v[0:1], s[8:9]
	v_readlane_b32 s100, v254, 3
	v_readlane_b32 s101, v254, 4
	s_nop 0
	v_mov_b32_e32 v0, s100
	v_mov_b32_e32 v1, s101
	s_getreg_b32 s3, hwreg(HW_REG_XCC_ID, 0, 4)
	s_waitcnt vmcnt(0)
	s_waitcnt lgkmcnt(0)
	s_barrier
	v_readlane_b32 s98, v254, 2
	v_readfirstlane_b32 s100, v176
	s_nop 0
	s_lshr_b32 s100, s100, 6
	s_cmp_eq_u32 s100, 1
	s_cselect_b32 s100, s98, 0
	s_cmp_lg_u32 s100, 0
	s_cbranch_scc0 .Lb21_ew_11
	buffer_inv sc1
	s_waitcnt vmcnt(0)

.LBB0_1104:
	s_mov_b64 s[8:9], s[0:1]
	s_waitcnt lgkmcnt(0)
	s_barrier
	s_nop 0
	v_mov_b64_e32 v[0:1], s[8:9]
	v_readlane_b32 s100, v254, 3
	v_readlane_b32 s101, v254, 4
	s_nop 0
	v_mov_b32_e32 v0, s100
	v_mov_b32_e32 v1, s101
	s_getreg_b32 s3, hwreg(HW_REG_XCC_ID, 0, 4)
	s_waitcnt vmcnt(0)
	s_waitcnt lgkmcnt(0)
	s_barrier
	v_readlane_b32 s98, v254, 2
	v_readfirstlane_b32 s100, v176
	s_nop 0
	s_lshr_b32 s100, s100, 6
	s_cmp_eq_u32 s100, 1
	s_cselect_b32 s100, s98, 0
	s_cmp_lg_u32 s100, 0
	s_cbranch_scc0 .Lew_11
	buffer_inv sc1
	s_waitcnt vmcnt(0)

.LBB0_1182:
	s_mov_b64 s[8:9], s[0:1]
	s_nop 0
	v_mov_b64_e32 v[0:1], s[8:9]
	v_readlane_b32 s100, v254, 3
	v_readlane_b32 s101, v254, 4
	s_nop 0
	v_mov_b32_e32 v0, s100
	v_mov_b32_e32 v1, s101
	s_getreg_b32 s3, hwreg(HW_REG_XCC_ID, 0, 4)
	s_waitcnt vmcnt(0)
	s_waitcnt lgkmcnt(0)
	s_barrier
	v_readlane_b32 s98, v254, 2
	v_readfirstlane_b32 s100, v176
	s_nop 0
	s_lshr_b32 s100, s100, 6
	s_cmp_eq_u32 s100, 1
	s_cselect_b32 s100, s98, 0
	s_cmp_lg_u32 s100, 0
	s_cbranch_scc0 .Lew_12
	buffer_inv sc1
	s_waitcnt vmcnt(0)
